# rwkv2 role 1 beta: raw-token LDS reads of all four rows issued together after the low-rank MFMAs
# baseline (speedup 1.0000x reference)
; __device__ unsigned long long rwkv2_phase(const Params& p, unsigned char* smem) {
;     ...
;                 if (prep) {
;                     float kkv[4], a_[4], eP[4], eTi[4];
;                     f32x4 accW = {0.f, 0.f, 0.f, 0.f}, accA = {0.f, 0.f, 0.f, 0.f};
; #pragma unroll
;                     for (int ks = 0; ks < 3; ++ks) { const bf16x8 afw = *(const bf16x8*)(twa + l15 * 104 + 32 * ks + 8 * lq), afa = *(const bf16x8*)(twa + (16 + l15) * 104 + 32 * ks + 8 * lq);
;                         const bf16x8 bwf = *(const bf16x8*)(W2t + k * 104 + 32 * ks + 8 * lq), baf = *(const bf16x8*)(A2t + k * 104 + 32 * ks + 8 * lq);
;                         accW = MFMA16(afw, bwf, accW); accA = MFMA16(afa, baf, accA); }
;                     float ld[4]; f32x4 cum = {0.f, 0.f, 0.f, 0.f};
; #pragma unroll
;                     for (int r = 0; r < 4; ++r) ld[r] = -0.60653066f * fsigmoid(w0k + accW[r]);
; #pragma unroll
;                     for (int r = 0; r < 4; ++r) cum = __builtin_amdgcn_mfma_f32_16x16x4f32((4 * lq + r <= l15) ? 1.0f : 0.0f, ld[r], cum, 0, 0, 0);
;                     float kmq[4], vq[4];
; #pragma unroll
;                     for (int r = 0; r < 4; ++r) { const int t = 4 * lq + r;
;                         const float rr = bf2f(raw[(0 * 17 + t + 1) * 64 + k]), rp_ = bf2f(raw[(0 * 17 + t) * 64 + k]);
;                         const float kr_ = bf2f(raw[(1 * 17 + t + 1) * 64 + k]), kp = bf2f(raw[(1 * 17 + t) * 64 + k]);
;                         const float vr = bf2f(raw[(2 * 17 + t + 1) * 64 + k]), vp = bf2f(raw[(2 * 17 + t) * 64 + k]);
;                         const float r_ = rr + (rp_ - rr) * mu_r, kx0 = kr_ + (kp - kr_) * mu_k, v_ = vr + (vp - vr) * mu_v;
;                         a_[r] = fsigmoid(a0k + accA[r]); kkv[r] = kx0 * kkk;
;                         const float kmod = kx0 * (1.0f + (a_[r] - 1.0f) * kak);
;                         const float eT = __expf(cum[r]); eTi[r] = __builtin_amdgcn_rcpf(eT); eP[r] = __expf(cum[r] - ld[r]);
;                         const float ssp = row16_sum(kkv[r] * kkv[r]), bop = row16_sum(r_ * kmod * rkk);
;                         if (l15 == 0) { ssP[t * 4 + w4] = ssp; bonP[t * 4 + w4] = bop; }
;                         Rt[t * 72 + k] = f2bf(r_ * eT); kmq[r] = kmod * eTi[r]; Kt[t * 72 + k] = f2bf(kmq[r]);
;                         Vf[t * 64 + k] = v_; vq[r] = v_;
.LBB0_981:
	s_bitcmp1_b32 s31, 0
	s_cselect_b32 s26, 0x2400, 0
	s_add_i32 s68, s26, 0
	s_mul_i32 s26, s31, 0xaaab
	s_lshr_b32 s26, s26, 17
	s_mul_i32 s26, s26, 3
	s_sub_i32 s26, s31, s26
	s_mulk_i32 s26, 0x2940
	s_and_b32 s26, s26, 0xffc0
	s_waitcnt lgkmcnt(0)
	s_barrier
	s_add_i32 s33, s26, 0
	v_cndmask_b32_e64 v42, 0, 1, s[28:29]
	v_and_b32_e32 v75, 15, v73
	v_ashrrev_i32_e32 v74, 4, v73
	s_add_i32 s62, s33, 0xe380
	v_cmp_ne_u32_e64 s[26:27], 1, v42
	s_andn2_b64 vcc, exec, s[28:29]
	s_cbranch_vccnz .LBB0_993
	v_mul_u32_u24_e32 v42, 0xd0, v75
	v_lshlrev_b32_e32 v46, 4, v74
	v_add3_u32 v96, 0, v42, v46
	ds_read_b128 v[42:45], v96 offset:33152
	v_add_u32_e32 v100, v131, v46
	ds_read_b128 v[46:49], v100
	ds_read_b128 v[56:59], v96 offset:33216
	ds_read_b128 v[76:79], v100 offset:64
	s_waitcnt lgkmcnt(2)
	v_mfma_f32_16x16x32_bf16 v[42:45], v[42:45], v[46:49], 0
	ds_read_b128 v[46:49], v96 offset:33280
	ds_read_b128 v[80:83], v100 offset:128
	ds_read_b128 v[84:87], v96 offset:36480
	ds_read_b128 v[88:91], v100 offset:13312
	s_waitcnt lgkmcnt(4)
	v_mfma_f32_16x16x32_bf16 v[42:45], v[56:59], v[76:79], v[42:45]
	v_lshlrev_b32_e32 v58, 2, v74
	v_sub_u32_e32 v56, v75, v58
	v_cmp_gt_i32_e32 vcc, 0, v56
	s_waitcnt lgkmcnt(2)
	v_mfma_f32_16x16x32_bf16 v[42:45], v[46:49], v[80:83], v[42:45]
	v_cndmask_b32_e64 v46, 1.0, 0, vcc
	v_cmp_gt_i32_e32 vcc, 1, v56
	s_waitcnt lgkmcnt(0)
	v_mfma_f32_16x16x32_bf16 v[82:85], v[84:87], v[88:91], 0
	v_mov_b32_e32 v87, 0
	s_waitcnt vmcnt(4)
	s_nop 1
	v_add_f32_e32 v42, v62, v42
	v_mul_f32_e32 v42, 0xbfb8aa3b, v42
	v_exp_f32_e32 v42, v42
	v_add_f32_e32 v43, v62, v43
	v_mul_f32_e32 v43, 0xbfb8aa3b, v43
	v_exp_f32_e32 v43, v43
	v_add_f32_e32 v42, 1.0, v42
	v_rcp_f32_e32 v42, v42
	v_add_f32_e32 v44, v62, v44
	v_add_f32_e32 v43, 1.0, v43
	v_rcp_f32_e32 v43, v43
	v_mul_f32_e32 v76, 0xbf1b4598, v42
	v_cndmask_b32_e64 v42, 1.0, 0, vcc
	v_mul_f32_e32 v44, 0xbfb8aa3b, v44
	v_mfma_f32_16x16x4_f32 v[46:49], v46, v76, 0
	v_exp_f32_e32 v44, v44
	v_mul_f32_e32 v57, 0xbf1b4598, v43
	v_cmp_gt_i32_e32 vcc, 2, v56
	v_add_f32_e32 v43, 1.0, v44
	v_rcp_f32_e32 v43, v43
	v_mfma_f32_16x16x4_f32 v[46:49], v42, v57, v[46:49]
	v_cndmask_b32_e64 v42, 1.0, 0, vcc
	v_mul_f32_e32 v77, 0xbf1b4598, v43
	v_cmp_gt_i32_e32 vcc, 3, v56
	s_nop 1
	v_cndmask_b32_e64 v56, 1.0, 0, vcc
	v_cmp_eq_u32_e32 vcc, 0, v75
	v_mfma_f32_16x16x4_f32 v[78:81], v42, v77, v[46:49]
	s_nop 1
	ds_read_b128 v[46:49], v96 offset:36544
	ds_read_b128 v[92:95], v100 offset:13376
	ds_read_b128 v[96:99], v96 offset:36608
	v_add_f32_e32 v42, v62, v45
	v_mul_f32_e32 v42, 0xbfb8aa3b, v42
	v_exp_f32_e32 v59, v42
	ds_read_b128 v[42:45], v100 offset:13440
	v_add_f32_e32 v59, 1.0, v59
	s_waitcnt lgkmcnt(2)
	v_mfma_f32_16x16x32_bf16 v[46:49], v[46:49], v[92:95], v[82:85]
	s_waitcnt lgkmcnt(0)
	v_mfma_f32_16x16x32_bf16 v[46:49], v[96:99], v[42:45], v[46:49]
	v_lshl_add_u32 v204, v74, 9, v152
	v_lshl_or_b32 v205, v74, 8, v102
	v_lshl_add_u32 v205, v205, 1, 0
	ds_read_u16 v180, v204 offset:26752
	ds_read_u16 v181, v205 offset:26624
	ds_read_u16 v182, v204 offset:28928
	ds_read_u16 v183, v204 offset:31104
	ds_read_u16 v184, v204 offset:30976
	ds_read_u16 v185, v204 offset:28800
	ds_read_u16 v186, v204 offset:26880
	ds_read_u16 v187, v205 offset:26752
	ds_read_u16 v188, v204 offset:29056
	ds_read_u16 v189, v204 offset:31232
	ds_read_u16 v190, v204 offset:31104
	ds_read_u16 v191, v204 offset:28928
	ds_read_u16 v192, v204 offset:27008
	ds_read_u16 v193, v205 offset:26880
	ds_read_u16 v194, v204 offset:29184
	ds_read_u16 v195, v204 offset:31360
	ds_read_u16 v196, v204 offset:31232
	ds_read_u16 v197, v204 offset:29056
	ds_read_u16 v198, v204 offset:27136
	ds_read_u16 v199, v205 offset:27008
	ds_read_u16 v200, v204 offset:29312
	ds_read_u16 v201, v204 offset:31488
	ds_read_u16 v202, v204 offset:31360
	ds_read_u16 v203, v204 offset:29184
	v_rcp_f32_e32 v42, v59
	s_nop 0
	v_mul_f32_e32 v59, 0xbf1b4598, v42
	s_nop 1
	v_mfma_f32_16x16x4_f32 v[42:45], v56, v59, v[78:81]
	v_lshl_or_b32 v56, v74, 8, v102
	v_lshl_add_u32 v78, v74, 9, v152
	v_lshl_add_u32 v79, v56, 1, 0
	s_waitcnt vmcnt(3)
	v_add_f32_e32 v46, v63, v46
	s_waitcnt lgkmcnt(0)
	v_mov_b32_e32 v81, v180
	v_mov_b32_e32 v79, v181
	v_mov_b32_e32 v83, v182
	v_mov_b32_e32 v80, v183
	v_mov_b32_e32 v82, v184
	v_mov_b32_e32 v78, v185
	v_mul_f32_e32 v46, 0xbfb8aa3b, v46
	v_exp_f32_e32 v46, v46
	s_waitcnt lgkmcnt(5)
	v_lshlrev_b32_e32 v81, 16, v81
	s_waitcnt lgkmcnt(4)
	v_lshlrev_b32_e32 v79, 16, v79
	s_waitcnt lgkmcnt(0)
	v_lshlrev_b32_e32 v84, 16, v78
	v_sub_f32_e32 v78, v79, v81
	v_add_f32_e32 v46, 1.0, v46
	v_fmac_f32_e32 v81, v3, v78
	v_rcp_f32_e32 v78, v46
	v_lshlrev_b32_e32 v83, 16, v83
	v_sub_f32_e32 v46, v84, v83
	v_fmac_f32_e32 v83, v60, v46
	v_add_f32_e32 v46, -1.0, v78
	s_waitcnt vmcnt(1)
	v_fma_f32 v46, v65, v46, 1.0
	v_mul_f32_e32 v79, v64, v83
	v_mul_f32_e32 v83, v46, v83
	v_mul_f32_e32 v85, v81, v83
	v_mul_f32_e32 v46, v79, v79
	v_mov_b32_e32 v84, 0
	s_waitcnt vmcnt(0)
	v_mul_f32_e32 v86, v66, v85
	v_mov_b32_dpp v84, v46 quad_perm:[1,0,3,2] row_mask:0xf bank_mask:0xf
	s_nop 0
	v_mov_b32_dpp v87, v86 quad_perm:[1,0,3,2] row_mask:0xf bank_mask:0xf
	v_fmac_f32_e32 v84, v79, v79
	v_fmac_f32_e32 v87, v66, v85
	v_mov_b32_e32 v86, 0
	v_add_f32_dpp v46, v84, v84 quad_perm:[2,3,0,1] row_mask:0xf bank_mask:0xf bound_ctrl:1
	v_add_f32_dpp v85, v87, v87 quad_perm:[2,3,0,1] row_mask:0xf bank_mask:0xf bound_ctrl:1
	v_mov_b32_e32 v84, 0
	v_add_f32_dpp v46, v46, v46 row_half_mirror row_mask:0xf bank_mask:0xf bound_ctrl:1
	v_add_f32_dpp v85, v85, v85 row_half_mirror row_mask:0xf bank_mask:0xf bound_ctrl:1
	s_nop 0
	v_mov_b32_dpp v84, v46 row_mirror row_mask:0xf bank_mask:0xf
	v_mov_b32_dpp v86, v85 row_mirror row_mask:0xf bank_mask:0xf
	s_and_saveexec_b64 s[28:29], vcc
	s_cbranch_execz .LBB0_984
	v_add_f32_e32 v46, v46, v84
	v_add_f32_e32 v84, v85, v86
	v_or_b32_e32 v85, s88, v73
	v_lshl_add_u32 v85, v85, 2, 0
	v_add_u32_e32 v86, 0x19b40, v85
	v_add_u32_e32 v85, 0x19c40, v85
	ds_write_b32 v86, v46
	ds_write_b32 v85, v84
